# v35: v31 + static priority stagger in the attention mixers: waves 4-7 at s_setprio 1 from the first MoBA unit, reset to 0 at every GEMM unit header
# speedup vs baseline: 1.0077x; 1.0029x over previous
.LBB0_223:
	s_setprio 0
	s_add_i32 s66, s66, 1
	s_mul_i32 s27, s66, s97
	s_mul_hi_u32 s30, s66, s96
	s_add_i32 s27, s30, s27
	s_mul_i32 s30, s66, s96
	s_add_u32 s30, s30, s2
	s_addc_u32 s31, s27, s61
	v_mov_b64_e32 v[2:3], 0x400
	v_cmp_lt_i64_e64 s[88:89], s[30:31], v[2:3]
	v_mov_b64_e32 v[2:3], 0x3ff
	v_cmp_gt_i64_e32 vcc, s[30:31], v[2:3]
	s_cbranch_vccnz .LBB0_229
	s_ashr_i32 s26, s30, 31
	s_lshr_b32 s26, s26, 29
	s_add_i32 s31, s30, s26
	s_and_b32 s26, s31, -8
	s_sub_i32 s30, s30, s26
	s_cmp_gt_i32 s30, -1
	s_mov_b64 s[26:27], -1
	s_cbranch_scc0 .LBB0_226
	s_lshl_b32 s34, s30, 7
	s_mov_b64 s[26:27], 0

.LBB0_297:
	s_setprio 0
	s_add_i32 s89, s89, 1
	s_mul_i32 s18, s89, s97
	s_mul_hi_u32 s19, s89, s96
	s_add_i32 s19, s19, s18
	s_mul_i32 s18, s89, s96
	s_add_u32 s22, s18, s2
	s_addc_u32 s23, s19, s61
	v_mov_b64_e32 v[2:3], s[36:37]
	v_cmp_ge_i64_e32 vcc, s[22:23], v[2:3]
	v_cmp_lt_i64_e64 s[38:39], s[22:23], v[2:3]
	s_cbranch_vccnz .LBB0_299
	s_ashr_i32 s18, s22, 31
	s_lshr_b32 s18, s18, 29
	s_add_i32 s18, s22, s18
	s_ashr_i32 s19, s18, 3
	s_and_b32 s18, s18, -8
	s_sub_i32 s18, s22, s18
	s_lshr_b32 s22, s18, 31
	s_or_b32 s22, s50, s22
	s_mul_i32 s18, s22, s18
	s_add_i32 s18, s18, s19
	s_abs_i32 s22, s18
	s_mul_hi_u32 s23, s22, s51
	s_mul_i32 s24, s23, s50
	s_sub_i32 s22, s22, s24
	s_ashr_i32 s19, s18, 31
	s_add_i32 s24, s23, 1
	s_sub_i32 s25, s22, s50
	s_cmp_ge_u32 s22, s50
	s_cselect_b32 s23, s24, s23
	s_cselect_b32 s22, s25, s22
	s_add_i32 s24, s23, 1
	s_cmp_ge_u32 s22, s50
	s_cselect_b32 s22, s24, s23
	s_xor_b32 s22, s22, s19
	s_sub_i32 s19, s22, s19
	s_lshl_b32 s22, s19, 2
	s_sub_i32 s23, 32, s22
	s_min_i32 s23, s23, 4
	s_abs_i32 s24, s23
	v_cvt_f32_u32_e32 v0, s24
	s_sub_i32 s26, 0, s24
	s_mul_i32 s19, s19, s50
	s_sub_i32 s18, s18, s19
	v_rcp_iflag_f32_e32 v0, v0
	s_abs_i32 s25, s18
	s_xor_b32 s19, s18, s23
	s_ashr_i32 s19, s19, 31
	v_mul_f32_e32 v0, 0x4f7ffffe, v0
	v_cvt_u32_f32_e32 v0, v0
	s_nop 0
	v_readfirstlane_b32 s27, v0
	s_mul_i32 s26, s26, s27
	s_mul_hi_u32 s26, s27, s26
	s_add_i32 s27, s27, s26
	s_mul_hi_u32 s26, s25, s27
	s_mul_i32 s27, s26, s24
	s_sub_i32 s25, s25, s27
	s_add_i32 s27, s26, 1
	s_sub_i32 s30, s25, s24
	s_cmp_ge_u32 s25, s24
	s_cselect_b32 s26, s27, s26
	s_cselect_b32 s25, s30, s25
	s_add_i32 s27, s26, 1
	s_cmp_ge_u32 s25, s24
	s_cselect_b32 s24, s27, s26
	s_xor_b32 s24, s24, s19
	s_sub_i32 s26, s24, s19
	s_mul_i32 s19, s26, s23
	s_sub_i32 s18, s18, s19
	s_add_i32 s48, s18, s22

.LBB0_449:
	s_bitcmp1_b32 s60, 8
	s_cbranch_scc0 .Lmixprio_skip
	s_setprio 1

.LBB0_570:
	s_setprio 0
	s_add_i32 s52, s52, 1
	s_mul_hi_u32 s19, s52, 0xaaaaaaab
	s_lshr_b32 s19, s19, 1
	s_mul_i32 s25, s19, s96
	s_mul_hi_i32 s23, s19, s96
	s_add_u32 s26, s25, s2
	s_addc_u32 s27, s23, s61
	v_mov_b64_e32 v[2:3], 0x200
	v_cmp_lt_i64_e64 s[40:41], s[26:27], v[2:3]
	v_mov_b64_e32 v[2:3], 0x1ff
	v_cmp_gt_i64_e32 vcc, s[26:27], v[2:3]
	s_cbranch_vccnz .LBB0_576
	s_ashr_i32 s22, s26, 31
	s_lshr_b32 s22, s22, 29
	s_add_i32 s24, s26, s22
	s_and_b32 s22, s24, -8
	s_sub_i32 s25, s26, s22
	s_cmp_gt_i32 s25, -1
	s_mov_b64 s[22:23], -1
	s_cbranch_scc0 .LBB0_573
	s_lshl_b32 s26, s25, 6
	s_mov_b64 s[22:23], 0

.LBB0_772:
	s_setprio 0
	s_add_i32 s52, s52, 1
	s_mul_i32 s23, s52, s97
	s_mul_hi_u32 s25, s52, s96
	s_add_i32 s25, s25, s23
	s_mul_i32 s23, s52, s96
	s_add_u32 s26, s23, s2
	s_addc_u32 s27, s25, s61
	v_mov_b64_e32 v[2:3], 0x200
	v_cmp_lt_i64_e64 s[40:41], s[26:27], v[2:3]
	v_mov_b64_e32 v[2:3], 0x1ff
	v_cmp_gt_i64_e32 vcc, s[26:27], v[2:3]
	s_cbranch_vccnz .LBB0_778
	s_ashr_i32 s22, s26, 31
	s_lshr_b32 s22, s22, 29
	s_add_i32 s24, s26, s22
	s_and_b32 s22, s24, -8
	s_sub_i32 s25, s26, s22
	s_cmp_gt_i32 s25, -1
	s_mov_b64 s[22:23], -1
	s_cbranch_scc0 .LBB0_775
	s_lshl_b32 s26, s25, 6
	s_mov_b64 s[22:23], 0

.LBB0_794:
	s_setprio 0
	s_add_i32 s46, s46, 1
	s_mul_i32 s23, s46, s97
	s_mul_hi_u32 s25, s46, s96
	s_add_i32 s25, s25, s23
	s_mul_i32 s23, s46, s96
	s_add_u32 s26, s23, s2
	s_addc_u32 s27, s25, s61
	v_mov_b64_e32 v[2:3], 0x200
	v_cmp_lt_i64_e64 s[38:39], s[26:27], v[2:3]
	v_mov_b64_e32 v[2:3], 0x1ff
	v_cmp_gt_i64_e32 vcc, s[26:27], v[2:3]
	s_cbranch_vccnz .LBB0_800
	s_ashr_i32 s22, s26, 31
	s_lshr_b32 s22, s22, 29
	s_add_i32 s24, s26, s22
	s_and_b32 s22, s24, -8
	s_sub_i32 s25, s26, s22
	s_cmp_gt_i32 s25, -1
	s_mov_b64 s[22:23], -1
	s_cbranch_scc0 .LBB0_797
	s_lshl_b32 s26, s25, 6
	s_mov_b64 s[22:23], 0
